# v13 with interleaved row share: each CU touches weight-tile rows i, i+8, i+16, ... (i = pm&7) instead of 32 contiguous rows
# speedup vs baseline: 1.0223x; 1.0000x over previous
.LBB0_340:
	s_and_b32 s99, s54, 7
	v_and_b32_e32 v244, 7, v0
	v_lshrrev_b32_e32 v245, 6, v0
	v_lshl_add_u32 v244, v245, 3, v244
	v_and_b32_e32 v245, 31, v244
	v_lshl_add_u32 v245, v245, 3, s99
	v_lshrrev_b32_e32 v246, 5, v244
	v_lshlrev_b32_e32 v245, 13, v245
	v_xor_b32_e32 v246, 1, v246
	v_lshl_add_u32 v250, v246, 7, v245
	v_mov_b32_e32 v251, 0
	v_add_u32_e32 v252, 0x10000, v159
	s_add_u32 s12, s12, 0x100080
	s_addc_u32 s13, s13, 0
	s_add_u32 s0, s14, 0x100
	v_mov_b32_e32 v2, 0
	s_addc_u32 s1, s15, 0
	s_mov_b32 s39, -2
	v_mov_b32_e32 v3, v2
	v_mov_b32_e32 v4, v2
	v_mov_b32_e32 v5, v2
	v_mov_b32_e32 v6, v2
	v_mov_b32_e32 v7, v2
	v_mov_b32_e32 v8, v2
	v_mov_b32_e32 v9, v2
	v_mov_b32_e32 v18, v2
	v_mov_b32_e32 v19, v2
	v_mov_b32_e32 v20, v2
	v_mov_b32_e32 v21, v2
	v_mov_b32_e32 v22, v2
	v_mov_b32_e32 v23, v2
	v_mov_b32_e32 v24, v2
	v_mov_b32_e32 v25, v2
	v_mov_b32_e32 v34, v2
	v_mov_b32_e32 v35, v2
	v_mov_b32_e32 v36, v2
	v_mov_b32_e32 v37, v2
	v_mov_b32_e32 v38, v2
	v_mov_b32_e32 v39, v2
	v_mov_b32_e32 v40, v2
	v_mov_b32_e32 v41, v2
	v_mov_b32_e32 v50, v2
	v_mov_b32_e32 v51, v2
	v_mov_b32_e32 v52, v2
	v_mov_b32_e32 v53, v2
	v_mov_b32_e32 v54, v2
	v_mov_b32_e32 v55, v2
	v_mov_b32_e32 v56, v2
	v_mov_b32_e32 v57, v2
	v_mov_b32_e32 v10, v2
	v_mov_b32_e32 v11, v2
	v_mov_b32_e32 v12, v2
	v_mov_b32_e32 v13, v2
	v_mov_b32_e32 v14, v2
	v_mov_b32_e32 v15, v2
	v_mov_b32_e32 v16, v2
	v_mov_b32_e32 v17, v2
	v_mov_b32_e32 v26, v2
	v_mov_b32_e32 v27, v2
	v_mov_b32_e32 v28, v2
	v_mov_b32_e32 v29, v2
	v_mov_b32_e32 v30, v2
	v_mov_b32_e32 v31, v2
	v_mov_b32_e32 v32, v2
	v_mov_b32_e32 v33, v2
	v_mov_b32_e32 v42, v2
	v_mov_b32_e32 v43, v2
	v_mov_b32_e32 v44, v2
	v_mov_b32_e32 v45, v2
	v_mov_b32_e32 v46, v2
	v_mov_b32_e32 v47, v2
	v_mov_b32_e32 v48, v2
	v_mov_b32_e32 v49, v2
	v_mov_b32_e32 v58, v2
	v_mov_b32_e32 v59, v2
	v_mov_b32_e32 v60, v2
	v_mov_b32_e32 v61, v2
	v_mov_b32_e32 v62, v2
	v_mov_b32_e32 v63, v2
	v_mov_b32_e32 v64, v2
	v_mov_b32_e32 v65, v2
	v_mov_b32_e32 v66, v2
	v_mov_b32_e32 v67, v2
	v_mov_b32_e32 v68, v2
	v_mov_b32_e32 v69, v2
	v_mov_b32_e32 v70, v2
	v_mov_b32_e32 v71, v2
	v_mov_b32_e32 v72, v2
	v_mov_b32_e32 v73, v2
	v_mov_b32_e32 v82, v2
	v_mov_b32_e32 v83, v2
	v_mov_b32_e32 v84, v2
	v_mov_b32_e32 v85, v2
	v_mov_b32_e32 v86, v2
	v_mov_b32_e32 v87, v2
	v_mov_b32_e32 v88, v2
	v_mov_b32_e32 v89, v2
	v_mov_b32_e32 v98, v2
	v_mov_b32_e32 v99, v2
	v_mov_b32_e32 v100, v2
	v_mov_b32_e32 v101, v2
	v_mov_b32_e32 v102, v2
	v_mov_b32_e32 v103, v2
	v_mov_b32_e32 v104, v2
	v_mov_b32_e32 v105, v2
	v_mov_b32_e32 v114, v2
	v_mov_b32_e32 v115, v2
	v_mov_b32_e32 v116, v2
	v_mov_b32_e32 v117, v2
	v_mov_b32_e32 v118, v2
	v_mov_b32_e32 v119, v2
	v_mov_b32_e32 v120, v2
	v_mov_b32_e32 v121, v2
	v_mov_b32_e32 v74, v2
	v_mov_b32_e32 v75, v2
	v_mov_b32_e32 v76, v2
	v_mov_b32_e32 v77, v2
	v_mov_b32_e32 v78, v2
	v_mov_b32_e32 v79, v2
	v_mov_b32_e32 v80, v2
	v_mov_b32_e32 v81, v2
	v_mov_b32_e32 v90, v2
	v_mov_b32_e32 v91, v2
	v_mov_b32_e32 v92, v2
	v_mov_b32_e32 v93, v2
	v_mov_b32_e32 v94, v2
	v_mov_b32_e32 v95, v2
	v_mov_b32_e32 v96, v2
	v_mov_b32_e32 v97, v2
	v_mov_b32_e32 v106, v2
	v_mov_b32_e32 v107, v2
	v_mov_b32_e32 v108, v2
	v_mov_b32_e32 v109, v2
	v_mov_b32_e32 v110, v2
	v_mov_b32_e32 v111, v2
	v_mov_b32_e32 v112, v2
	v_mov_b32_e32 v113, v2
	v_mov_b32_e32 v122, v2
	v_mov_b32_e32 v123, v2
	v_mov_b32_e32 v124, v2
	v_mov_b32_e32 v125, v2
	v_mov_b32_e32 v126, v2
	v_mov_b32_e32 v127, v2
	v_mov_b32_e32 v128, v2
	v_mov_b32_e32 v129, v2

.LBB0_571:
	s_and_b32 s99, s46, 7
	v_and_b32_e32 v244, 7, v0
	v_lshrrev_b32_e32 v245, 6, v0
	v_lshl_add_u32 v244, v245, 3, v244
	v_and_b32_e32 v245, 31, v244
	v_lshl_add_u32 v245, v245, 3, s99
	v_lshrrev_b32_e32 v246, 5, v244
	v_lshlrev_b32_e32 v245, 13, v245
	v_xor_b32_e32 v246, 1, v246
	v_lshl_add_u32 v250, v246, 7, v245
	v_mov_b32_e32 v251, 0
	v_add_u32_e32 v252, 0x10000, v159
	s_add_u32 s12, s12, 0x100080
	s_addc_u32 s13, s13, 0
	s_add_u32 s0, s14, 0x100
	v_mov_b32_e32 v2, 0
	s_addc_u32 s1, s15, 0
	s_mov_b32 s35, -2
	v_mov_b32_e32 v3, v2
	v_mov_b32_e32 v4, v2
	v_mov_b32_e32 v5, v2
	v_mov_b32_e32 v6, v2
	v_mov_b32_e32 v7, v2
	v_mov_b32_e32 v8, v2
	v_mov_b32_e32 v9, v2
	v_mov_b32_e32 v18, v2
	v_mov_b32_e32 v19, v2
	v_mov_b32_e32 v20, v2
	v_mov_b32_e32 v21, v2
	v_mov_b32_e32 v22, v2
	v_mov_b32_e32 v23, v2
	v_mov_b32_e32 v24, v2
	v_mov_b32_e32 v25, v2
	v_mov_b32_e32 v34, v2
	v_mov_b32_e32 v35, v2
	v_mov_b32_e32 v36, v2
	v_mov_b32_e32 v37, v2
	v_mov_b32_e32 v38, v2
	v_mov_b32_e32 v39, v2
	v_mov_b32_e32 v40, v2
	v_mov_b32_e32 v41, v2
	v_mov_b32_e32 v50, v2
	v_mov_b32_e32 v51, v2
	v_mov_b32_e32 v52, v2
	v_mov_b32_e32 v53, v2
	v_mov_b32_e32 v54, v2
	v_mov_b32_e32 v55, v2
	v_mov_b32_e32 v56, v2
	v_mov_b32_e32 v57, v2
	v_mov_b32_e32 v10, v2
	v_mov_b32_e32 v11, v2
	v_mov_b32_e32 v12, v2
	v_mov_b32_e32 v13, v2
	v_mov_b32_e32 v14, v2
	v_mov_b32_e32 v15, v2
	v_mov_b32_e32 v16, v2
	v_mov_b32_e32 v17, v2
	v_mov_b32_e32 v26, v2
	v_mov_b32_e32 v27, v2
	v_mov_b32_e32 v28, v2
	v_mov_b32_e32 v29, v2
	v_mov_b32_e32 v30, v2
	v_mov_b32_e32 v31, v2
	v_mov_b32_e32 v32, v2
	v_mov_b32_e32 v33, v2
	v_mov_b32_e32 v42, v2
	v_mov_b32_e32 v43, v2
	v_mov_b32_e32 v44, v2
	v_mov_b32_e32 v45, v2
	v_mov_b32_e32 v46, v2
	v_mov_b32_e32 v47, v2
	v_mov_b32_e32 v48, v2
	v_mov_b32_e32 v49, v2
	v_mov_b32_e32 v58, v2
	v_mov_b32_e32 v59, v2
	v_mov_b32_e32 v60, v2
	v_mov_b32_e32 v61, v2
	v_mov_b32_e32 v62, v2
	v_mov_b32_e32 v63, v2
	v_mov_b32_e32 v64, v2
	v_mov_b32_e32 v65, v2
	v_mov_b32_e32 v66, v2
	v_mov_b32_e32 v67, v2
	v_mov_b32_e32 v68, v2
	v_mov_b32_e32 v69, v2
	v_mov_b32_e32 v70, v2
	v_mov_b32_e32 v71, v2
	v_mov_b32_e32 v72, v2
	v_mov_b32_e32 v73, v2
	v_mov_b32_e32 v82, v2
	v_mov_b32_e32 v83, v2
	v_mov_b32_e32 v84, v2
	v_mov_b32_e32 v85, v2
	v_mov_b32_e32 v86, v2
	v_mov_b32_e32 v87, v2
	v_mov_b32_e32 v88, v2
	v_mov_b32_e32 v89, v2
	v_mov_b32_e32 v98, v2
	v_mov_b32_e32 v99, v2
	v_mov_b32_e32 v100, v2
	v_mov_b32_e32 v101, v2
	v_mov_b32_e32 v102, v2
	v_mov_b32_e32 v103, v2
	v_mov_b32_e32 v104, v2
	v_mov_b32_e32 v105, v2
	v_mov_b32_e32 v114, v2
	v_mov_b32_e32 v115, v2
	v_mov_b32_e32 v116, v2
	v_mov_b32_e32 v117, v2
	v_mov_b32_e32 v118, v2
	v_mov_b32_e32 v119, v2
	v_mov_b32_e32 v120, v2
	v_mov_b32_e32 v121, v2
	v_mov_b32_e32 v74, v2
	v_mov_b32_e32 v75, v2
	v_mov_b32_e32 v76, v2
	v_mov_b32_e32 v77, v2
	v_mov_b32_e32 v78, v2
	v_mov_b32_e32 v79, v2
	v_mov_b32_e32 v80, v2
	v_mov_b32_e32 v81, v2
	v_mov_b32_e32 v90, v2
	v_mov_b32_e32 v91, v2
	v_mov_b32_e32 v92, v2
	v_mov_b32_e32 v93, v2
	v_mov_b32_e32 v94, v2
	v_mov_b32_e32 v95, v2
	v_mov_b32_e32 v96, v2
	v_mov_b32_e32 v97, v2
	v_mov_b32_e32 v106, v2
	v_mov_b32_e32 v107, v2
	v_mov_b32_e32 v108, v2
	v_mov_b32_e32 v109, v2
	v_mov_b32_e32 v110, v2
	v_mov_b32_e32 v111, v2
	v_mov_b32_e32 v112, v2
	v_mov_b32_e32 v113, v2
	v_mov_b32_e32 v122, v2
	v_mov_b32_e32 v123, v2
	v_mov_b32_e32 v124, v2
	v_mov_b32_e32 v125, v2
	v_mov_b32_e32 v126, v2
	v_mov_b32_e32 v127, v2
	v_mov_b32_e32 v128, v2
	v_mov_b32_e32 v129, v2

.LBB0_881:
	s_and_b32 s99, s28, 7
	v_and_b32_e32 v244, 7, v0
	v_lshrrev_b32_e32 v245, 6, v0
	v_lshl_add_u32 v244, v245, 3, v244
	v_and_b32_e32 v245, 31, v244
	v_lshl_add_u32 v245, v245, 3, s99
	v_lshrrev_b32_e32 v246, 5, v244
	v_lshlrev_b32_e32 v245, 13, v245
	v_xor_b32_e32 v246, 1, v246
	v_lshl_add_u32 v250, v246, 7, v245
	v_mov_b32_e32 v251, 0
	v_add_u32_e32 v252, 0x10000, v155
	s_add_u32 s10, s10, 0x100080
	s_addc_u32 s11, s11, 0
	s_add_u32 s0, s38, 0x100
	v_mov_b32_e32 v4, 0
	s_addc_u32 s1, s39, 0
	s_mov_b32 s12, -2
	v_mov_b32_e32 v5, v4
	v_mov_b32_e32 v6, v4
	v_mov_b32_e32 v7, v4
	v_mov_b32_e32 v8, v4
	v_mov_b32_e32 v9, v4
	v_mov_b32_e32 v10, v4
	v_mov_b32_e32 v11, v4
	v_mov_b32_e32 v20, v4
	v_mov_b32_e32 v21, v4
	v_mov_b32_e32 v22, v4
	v_mov_b32_e32 v23, v4
	v_mov_b32_e32 v24, v4
	v_mov_b32_e32 v25, v4
	v_mov_b32_e32 v26, v4
	v_mov_b32_e32 v27, v4
	v_mov_b32_e32 v36, v4
	v_mov_b32_e32 v37, v4
	v_mov_b32_e32 v38, v4
	v_mov_b32_e32 v39, v4
	v_mov_b32_e32 v40, v4
	v_mov_b32_e32 v41, v4
	v_mov_b32_e32 v42, v4
	v_mov_b32_e32 v43, v4
	v_mov_b32_e32 v52, v4
	v_mov_b32_e32 v53, v4
	v_mov_b32_e32 v54, v4
	v_mov_b32_e32 v55, v4
	v_mov_b32_e32 v56, v4
	v_mov_b32_e32 v57, v4
	v_mov_b32_e32 v58, v4
	v_mov_b32_e32 v59, v4
	v_mov_b32_e32 v12, v4
	v_mov_b32_e32 v13, v4
	v_mov_b32_e32 v14, v4
	v_mov_b32_e32 v15, v4
	v_mov_b32_e32 v16, v4
	v_mov_b32_e32 v17, v4
	v_mov_b32_e32 v18, v4
	v_mov_b32_e32 v19, v4
	v_mov_b32_e32 v28, v4
	v_mov_b32_e32 v29, v4
	v_mov_b32_e32 v30, v4
	v_mov_b32_e32 v31, v4
	v_mov_b32_e32 v32, v4
	v_mov_b32_e32 v33, v4
	v_mov_b32_e32 v34, v4
	v_mov_b32_e32 v35, v4
	v_mov_b32_e32 v44, v4
	v_mov_b32_e32 v45, v4
	v_mov_b32_e32 v46, v4
	v_mov_b32_e32 v47, v4
	v_mov_b32_e32 v48, v4
	v_mov_b32_e32 v49, v4
	v_mov_b32_e32 v50, v4
	v_mov_b32_e32 v51, v4
	v_mov_b32_e32 v60, v4
	v_mov_b32_e32 v61, v4
	v_mov_b32_e32 v62, v4
	v_mov_b32_e32 v63, v4
	v_mov_b32_e32 v64, v4
	v_mov_b32_e32 v65, v4
	v_mov_b32_e32 v66, v4
	v_mov_b32_e32 v67, v4
	v_mov_b32_e32 v68, v4
	v_mov_b32_e32 v69, v4
	v_mov_b32_e32 v70, v4
	v_mov_b32_e32 v71, v4
	v_mov_b32_e32 v72, v4
	v_mov_b32_e32 v73, v4
	v_mov_b32_e32 v74, v4
	v_mov_b32_e32 v75, v4
	v_mov_b32_e32 v84, v4
	v_mov_b32_e32 v85, v4
	v_mov_b32_e32 v86, v4
	v_mov_b32_e32 v87, v4
	v_mov_b32_e32 v88, v4
	v_mov_b32_e32 v89, v4
	v_mov_b32_e32 v90, v4
	v_mov_b32_e32 v91, v4
	v_mov_b32_e32 v100, v4
	v_mov_b32_e32 v101, v4
	v_mov_b32_e32 v102, v4
	v_mov_b32_e32 v103, v4
	v_mov_b32_e32 v104, v4
	v_mov_b32_e32 v105, v4
	v_mov_b32_e32 v106, v4
	v_mov_b32_e32 v107, v4
	v_mov_b32_e32 v116, v4
	v_mov_b32_e32 v117, v4
	v_mov_b32_e32 v118, v4
	v_mov_b32_e32 v119, v4
	v_mov_b32_e32 v120, v4
	v_mov_b32_e32 v121, v4
	v_mov_b32_e32 v122, v4
	v_mov_b32_e32 v123, v4
	v_mov_b32_e32 v76, v4
	v_mov_b32_e32 v77, v4
	v_mov_b32_e32 v78, v4
	v_mov_b32_e32 v79, v4
	v_mov_b32_e32 v80, v4
	v_mov_b32_e32 v81, v4
	v_mov_b32_e32 v82, v4
	v_mov_b32_e32 v83, v4
	v_mov_b32_e32 v92, v4
	v_mov_b32_e32 v93, v4
	v_mov_b32_e32 v94, v4
	v_mov_b32_e32 v95, v4
	v_mov_b32_e32 v96, v4
	v_mov_b32_e32 v97, v4
	v_mov_b32_e32 v98, v4
	v_mov_b32_e32 v99, v4
	v_mov_b32_e32 v108, v4
	v_mov_b32_e32 v109, v4
	v_mov_b32_e32 v110, v4
	v_mov_b32_e32 v111, v4
	v_mov_b32_e32 v112, v4
	v_mov_b32_e32 v113, v4
	v_mov_b32_e32 v114, v4
	v_mov_b32_e32 v115, v4
	v_mov_b32_e32 v124, v4
	v_mov_b32_e32 v125, v4
	v_mov_b32_e32 v126, v4
	v_mov_b32_e32 v127, v4
	v_mov_b32_e32 v128, v4
	v_mov_b32_e32 v129, v4
	v_mov_b32_e32 v130, v4
	v_mov_b32_e32 v131, v4

.LBB0_1225:
	s_and_b32 s99, s58, 7
	v_and_b32_e32 v244, 7, v0
	v_lshrrev_b32_e32 v245, 6, v0
	v_lshl_add_u32 v244, v245, 3, v244
	v_and_b32_e32 v245, 31, v244
	v_lshl_add_u32 v245, v245, 3, s99
	v_lshrrev_b32_e32 v246, 5, v244
	v_lshlrev_b32_e32 v245, 13, v245
	v_xor_b32_e32 v246, 1, v246
	v_lshl_add_u32 v250, v246, 7, v245
	v_mov_b32_e32 v251, 0
	v_add_u32_e32 v252, 0x10000, v151
	s_add_u32 s10, s10, 0x100080
	s_addc_u32 s11, s11, 0
	s_add_u32 s0, s28, 0x100
	v_mov_b32_e32 v4, 0
	s_addc_u32 s1, s29, 0
	s_mov_b32 s20, -2
	v_mov_b32_e32 v5, v4
	v_mov_b32_e32 v6, v4
	v_mov_b32_e32 v7, v4
	v_mov_b32_e32 v8, v4
	v_mov_b32_e32 v9, v4
	v_mov_b32_e32 v10, v4
	v_mov_b32_e32 v11, v4
	v_mov_b32_e32 v20, v4
	v_mov_b32_e32 v21, v4
	v_mov_b32_e32 v22, v4
	v_mov_b32_e32 v23, v4
	v_mov_b32_e32 v24, v4
	v_mov_b32_e32 v25, v4
	v_mov_b32_e32 v26, v4
	v_mov_b32_e32 v27, v4
	v_mov_b32_e32 v36, v4
	v_mov_b32_e32 v37, v4
	v_mov_b32_e32 v38, v4
	v_mov_b32_e32 v39, v4
	v_mov_b32_e32 v40, v4
	v_mov_b32_e32 v41, v4
	v_mov_b32_e32 v42, v4
	v_mov_b32_e32 v43, v4
	v_mov_b32_e32 v52, v4
	v_mov_b32_e32 v53, v4
	v_mov_b32_e32 v54, v4
	v_mov_b32_e32 v55, v4
	v_mov_b32_e32 v56, v4
	v_mov_b32_e32 v57, v4
	v_mov_b32_e32 v58, v4
	v_mov_b32_e32 v59, v4
	v_mov_b32_e32 v12, v4
	v_mov_b32_e32 v13, v4
	v_mov_b32_e32 v14, v4
	v_mov_b32_e32 v15, v4
	v_mov_b32_e32 v16, v4
	v_mov_b32_e32 v17, v4
	v_mov_b32_e32 v18, v4
	v_mov_b32_e32 v19, v4
	v_mov_b32_e32 v28, v4
	v_mov_b32_e32 v29, v4
	v_mov_b32_e32 v30, v4
	v_mov_b32_e32 v31, v4
	v_mov_b32_e32 v32, v4
	v_mov_b32_e32 v33, v4
	v_mov_b32_e32 v34, v4
	v_mov_b32_e32 v35, v4
	v_mov_b32_e32 v44, v4
	v_mov_b32_e32 v45, v4
	v_mov_b32_e32 v46, v4
	v_mov_b32_e32 v47, v4
	v_mov_b32_e32 v48, v4
	v_mov_b32_e32 v49, v4
	v_mov_b32_e32 v50, v4
	v_mov_b32_e32 v51, v4
	v_mov_b32_e32 v60, v4
	v_mov_b32_e32 v61, v4
	v_mov_b32_e32 v62, v4
	v_mov_b32_e32 v63, v4
	v_mov_b32_e32 v64, v4
	v_mov_b32_e32 v65, v4
	v_mov_b32_e32 v66, v4
	v_mov_b32_e32 v67, v4
	v_mov_b32_e32 v68, v4
	v_mov_b32_e32 v69, v4
	v_mov_b32_e32 v70, v4
	v_mov_b32_e32 v71, v4
	v_mov_b32_e32 v72, v4
	v_mov_b32_e32 v73, v4
	v_mov_b32_e32 v74, v4
	v_mov_b32_e32 v75, v4
	v_mov_b32_e32 v84, v4
	v_mov_b32_e32 v85, v4
	v_mov_b32_e32 v86, v4
	v_mov_b32_e32 v87, v4
	v_mov_b32_e32 v88, v4
	v_mov_b32_e32 v89, v4
	v_mov_b32_e32 v90, v4
	v_mov_b32_e32 v91, v4
	v_mov_b32_e32 v100, v4
	v_mov_b32_e32 v101, v4
	v_mov_b32_e32 v102, v4
	v_mov_b32_e32 v103, v4
	v_mov_b32_e32 v104, v4
	v_mov_b32_e32 v105, v4
	v_mov_b32_e32 v106, v4
	v_mov_b32_e32 v107, v4
	v_mov_b32_e32 v116, v4
	v_mov_b32_e32 v117, v4
	v_mov_b32_e32 v118, v4
	v_mov_b32_e32 v119, v4
	v_mov_b32_e32 v120, v4
	v_mov_b32_e32 v121, v4
	v_mov_b32_e32 v122, v4
	v_mov_b32_e32 v123, v4
	v_mov_b32_e32 v76, v4
	v_mov_b32_e32 v77, v4
	v_mov_b32_e32 v78, v4
	v_mov_b32_e32 v79, v4
	v_mov_b32_e32 v80, v4
	v_mov_b32_e32 v81, v4
	v_mov_b32_e32 v82, v4
	v_mov_b32_e32 v83, v4
	v_mov_b32_e32 v92, v4
	v_mov_b32_e32 v93, v4
	v_mov_b32_e32 v94, v4
	v_mov_b32_e32 v95, v4
	v_mov_b32_e32 v96, v4
	v_mov_b32_e32 v97, v4
	v_mov_b32_e32 v98, v4
	v_mov_b32_e32 v99, v4
	v_mov_b32_e32 v108, v4
	v_mov_b32_e32 v109, v4
	v_mov_b32_e32 v110, v4
	v_mov_b32_e32 v111, v4
	v_mov_b32_e32 v112, v4
	v_mov_b32_e32 v113, v4
	v_mov_b32_e32 v114, v4
	v_mov_b32_e32 v115, v4
	v_mov_b32_e32 v124, v4
	v_mov_b32_e32 v125, v4
	v_mov_b32_e32 v126, v4
	v_mov_b32_e32 v127, v4
	v_mov_b32_e32 v128, v4
	v_mov_b32_e32 v129, v4
	v_mov_b32_e32 v130, v4
	v_mov_b32_e32 v131, v4
